# out-projection main loop: head-boundary rescale reads its eight per-row ratios in one batch (one LDS round trip, counted waits) instead of eight serialized read-wait-multiply groups
# speedup vs baseline: 1.0180x; 1.0038x over previous
.LBB0_1257:
	s_add_i32 s22, s82, -4
	s_cmp_gt_u32 s22, 12
	s_cselect_b64 s[22:23], -1, 0
	s_bitcmp1_b32 s82, 1
	s_cselect_b64 vcc, -1, 0
	s_or_b64 s[22:23], s[22:23], vcc
	s_and_b64 vcc, exec, s[22:23]
	s_cbranch_vccnz .LBB0_1259
	v_add_u32_e32 v141, s44, v139
	v_add_u32_e32 v141, 0x21a00, v141
	ds_read_b32 v142, v141
	ds_read_b32 v144, v141 offset:64
	ds_read_b32 v146, v141 offset:128
	ds_read_b32 v148, v141 offset:192
	ds_read_b32 v150, v141 offset:512
	ds_read_b32 v152, v141 offset:576
	ds_read_b32 v154, v141 offset:640
	ds_read_b32 v156, v141 offset:704
	s_waitcnt lgkmcnt(7)
	v_pk_mul_f32 v[126:127], v[126:127], v[142:143] op_sel_hi:[1,0]
	v_pk_mul_f32 v[124:125], v[124:125], v[142:143] op_sel_hi:[1,0]
	v_pk_mul_f32 v[122:123], v[122:123], v[142:143] op_sel_hi:[1,0]
	v_pk_mul_f32 v[120:121], v[120:121], v[142:143] op_sel_hi:[1,0]
	v_pk_mul_f32 v[118:119], v[118:119], v[142:143] op_sel_hi:[1,0]
	v_pk_mul_f32 v[116:117], v[116:117], v[142:143] op_sel_hi:[1,0]
	v_pk_mul_f32 v[114:115], v[114:115], v[142:143] op_sel_hi:[1,0]
	v_pk_mul_f32 v[112:113], v[112:113], v[142:143] op_sel_hi:[1,0]
	s_waitcnt lgkmcnt(6)
	v_pk_mul_f32 v[110:111], v[110:111], v[144:145] op_sel_hi:[1,0]
	v_pk_mul_f32 v[108:109], v[108:109], v[144:145] op_sel_hi:[1,0]
	v_pk_mul_f32 v[106:107], v[106:107], v[144:145] op_sel_hi:[1,0]
	v_pk_mul_f32 v[104:105], v[104:105], v[144:145] op_sel_hi:[1,0]
	v_pk_mul_f32 v[102:103], v[102:103], v[144:145] op_sel_hi:[1,0]
	v_pk_mul_f32 v[100:101], v[100:101], v[144:145] op_sel_hi:[1,0]
	v_pk_mul_f32 v[98:99], v[98:99], v[144:145] op_sel_hi:[1,0]
	v_pk_mul_f32 v[96:97], v[96:97], v[144:145] op_sel_hi:[1,0]
	s_waitcnt lgkmcnt(5)
	v_pk_mul_f32 v[94:95], v[94:95], v[146:147] op_sel_hi:[1,0]
	v_pk_mul_f32 v[92:93], v[92:93], v[146:147] op_sel_hi:[1,0]
	v_pk_mul_f32 v[90:91], v[90:91], v[146:147] op_sel_hi:[1,0]
	v_pk_mul_f32 v[88:89], v[88:89], v[146:147] op_sel_hi:[1,0]
	v_pk_mul_f32 v[86:87], v[86:87], v[146:147] op_sel_hi:[1,0]
	v_pk_mul_f32 v[84:85], v[84:85], v[146:147] op_sel_hi:[1,0]
	v_pk_mul_f32 v[82:83], v[82:83], v[146:147] op_sel_hi:[1,0]
	v_pk_mul_f32 v[80:81], v[80:81], v[146:147] op_sel_hi:[1,0]
	s_waitcnt lgkmcnt(4)
	v_pk_mul_f32 v[78:79], v[78:79], v[148:149] op_sel_hi:[1,0]
	v_pk_mul_f32 v[76:77], v[76:77], v[148:149] op_sel_hi:[1,0]
	v_pk_mul_f32 v[74:75], v[74:75], v[148:149] op_sel_hi:[1,0]
	v_pk_mul_f32 v[72:73], v[72:73], v[148:149] op_sel_hi:[1,0]
	v_pk_mul_f32 v[70:71], v[70:71], v[148:149] op_sel_hi:[1,0]
	v_pk_mul_f32 v[68:69], v[68:69], v[148:149] op_sel_hi:[1,0]
	v_pk_mul_f32 v[66:67], v[66:67], v[148:149] op_sel_hi:[1,0]
	v_pk_mul_f32 v[64:65], v[64:65], v[148:149] op_sel_hi:[1,0]
	s_waitcnt lgkmcnt(3)
	v_pk_mul_f32 v[62:63], v[62:63], v[150:151] op_sel_hi:[1,0]
	v_pk_mul_f32 v[60:61], v[60:61], v[150:151] op_sel_hi:[1,0]
	v_pk_mul_f32 v[58:59], v[58:59], v[150:151] op_sel_hi:[1,0]
	v_pk_mul_f32 v[56:57], v[56:57], v[150:151] op_sel_hi:[1,0]
	v_pk_mul_f32 v[54:55], v[54:55], v[150:151] op_sel_hi:[1,0]
	v_pk_mul_f32 v[52:53], v[52:53], v[150:151] op_sel_hi:[1,0]
	v_pk_mul_f32 v[50:51], v[50:51], v[150:151] op_sel_hi:[1,0]
	v_pk_mul_f32 v[48:49], v[48:49], v[150:151] op_sel_hi:[1,0]
	s_waitcnt lgkmcnt(2)
	v_pk_mul_f32 v[46:47], v[46:47], v[152:153] op_sel_hi:[1,0]
	v_pk_mul_f32 v[44:45], v[44:45], v[152:153] op_sel_hi:[1,0]
	v_pk_mul_f32 v[42:43], v[42:43], v[152:153] op_sel_hi:[1,0]
	v_pk_mul_f32 v[40:41], v[40:41], v[152:153] op_sel_hi:[1,0]
	v_pk_mul_f32 v[38:39], v[38:39], v[152:153] op_sel_hi:[1,0]
	v_pk_mul_f32 v[36:37], v[36:37], v[152:153] op_sel_hi:[1,0]
	v_pk_mul_f32 v[34:35], v[34:35], v[152:153] op_sel_hi:[1,0]
	v_pk_mul_f32 v[32:33], v[32:33], v[152:153] op_sel_hi:[1,0]
	s_waitcnt lgkmcnt(1)
	v_pk_mul_f32 v[30:31], v[30:31], v[154:155] op_sel_hi:[1,0]
	v_pk_mul_f32 v[28:29], v[28:29], v[154:155] op_sel_hi:[1,0]
	v_pk_mul_f32 v[26:27], v[26:27], v[154:155] op_sel_hi:[1,0]
	v_pk_mul_f32 v[24:25], v[24:25], v[154:155] op_sel_hi:[1,0]
	v_pk_mul_f32 v[22:23], v[22:23], v[154:155] op_sel_hi:[1,0]
	v_pk_mul_f32 v[20:21], v[20:21], v[154:155] op_sel_hi:[1,0]
	v_pk_mul_f32 v[18:19], v[18:19], v[154:155] op_sel_hi:[1,0]
	v_pk_mul_f32 v[16:17], v[16:17], v[154:155] op_sel_hi:[1,0]
	s_waitcnt lgkmcnt(0)
	v_pk_mul_f32 v[14:15], v[14:15], v[156:157] op_sel_hi:[1,0]
	v_pk_mul_f32 v[12:13], v[12:13], v[156:157] op_sel_hi:[1,0]
	v_pk_mul_f32 v[10:11], v[10:11], v[156:157] op_sel_hi:[1,0]
	v_pk_mul_f32 v[8:9], v[8:9], v[156:157] op_sel_hi:[1,0]
	v_pk_mul_f32 v[6:7], v[6:7], v[156:157] op_sel_hi:[1,0]
	v_pk_mul_f32 v[4:5], v[4:5], v[156:157] op_sel_hi:[1,0]
	v_pk_mul_f32 v[2:3], v[2:3], v[156:157] op_sel_hi:[1,0]
	v_pk_mul_f32 v[0:1], v[0:1], v[156:157] op_sel_hi:[1,0]
